# P4 chain loop: vmcnt(0) drain moved off the per-step path onto the state-reload path only; counted vmcnt(8)/(4) before staged-register use
# speedup vs baseline: 1.0073x; 1.0073x over previous
.LBB0_614:
	s_mul_i32 s9, s52, 0x4400
	ds_read_b128 v[102:105], v193 offset:31232
	ds_read_b128 v[106:109], v192 offset:48640
	v_add_u32_e32 v159, s9, v190
	ds_read_b128 v[110:113], v192 offset:48704
	ds_read_b128 v[114:117], v193 offset:31296
	ds_read_b128 v[198:201], v159
	ds_read_b128 v[202:205], v159 offset:64
	s_waitcnt lgkmcnt(0)
	v_mfma_f32_16x16x32_bf16 v[102:105], v[102:105], v[106:109], 0
	s_mul_i32 s9, s52, 0x500
	s_add_i32 s87, s9, 0
	s_add_i32 s87, s87, 0x1d400
	s_waitcnt lgkmcnt(1)
	v_mfma_f32_16x16x32_bf16 v[106:109], v[198:201], v[106:109], 0
	s_cmp_lg_u32 s8, 0
	s_cselect_b64 s[10:11], -1, 0
	s_cmp_eq_u32 s8, 0
	v_mfma_f32_16x16x32_bf16 v[102:105], v[114:117], v[110:113], v[102:105]
	ds_read_b128 v[114:117], v193 offset:31360
	ds_read_b128 v[198:201], v192 offset:48768
	s_waitcnt lgkmcnt(2)
	v_mfma_f32_16x16x32_bf16 v[106:109], v[202:205], v[110:113], v[106:109]
	ds_read_b128 v[110:113], v193 offset:31424
	ds_read_b128 v[202:205], v192 offset:48832
	s_waitcnt lgkmcnt(2)
	v_mfma_f32_16x16x32_bf16 v[102:105], v[114:117], v[198:201], v[102:105]
	ds_read_b128 v[114:117], v159 offset:128
	ds_read_b128 v[206:209], v159 offset:192
	v_lshl_add_u32 v159, v189, 2, s87
	s_waitcnt lgkmcnt(2)
	v_mfma_f32_16x16x32_bf16 v[102:105], v[110:113], v[202:205], v[102:105]
	ds_read_b128 v[110:113], v159 offset:512
	s_waitcnt lgkmcnt(2)
	v_mfma_f32_16x16x32_bf16 v[106:109], v[114:117], v[198:201], v[106:109]
	s_nop 4
	v_sub_f32_e32 v105, v101, v105
	v_sub_f32_e32 v104, v100, v104
	v_sub_f32_e32 v103, v99, v103
	v_sub_f32_e32 v102, v98, v102
	v_cvt_pk_bf16_f32 v114, v102, v103
	s_waitcnt lgkmcnt(0)
	v_pk_mul_f32 v[102:103], v[102:103], v[110:111]
	v_cvt_pk_bf16_f32 v115, v104, v105
	v_pk_mul_f32 v[104:105], v[104:105], v[112:113]
	v_cvt_pk_bf16_f32 v102, v102, v103
	v_cvt_pk_bf16_f32 v103, v104, v105
	ds_write2st64_b64 v194, v[114:115], v[102:103] offset0:112 offset1:121
	ds_read_b128 v[110:113], v159
	v_mfma_f32_16x16x32_bf16 v[114:117], v[206:209], v[202:205], v[106:109]
	s_cbranch_scc1 .LBB0_646
	s_xor_b32 s14, s52, 1
	s_cmp_eq_u32 s27, 0
	s_mul_i32 s8, s14, 0x4400
	s_cselect_b64 vcc, -1, 0
	v_add_u32_e32 v102, s8, v169
	v_cndmask_b32_e32 v106, v162, v161, vcc
	v_cndmask_b32_e32 v107, v164, v163, vcc
	v_cndmask_b32_e32 v108, v166, v165, vcc
	v_cndmask_b32_e32 v109, v168, v167, vcc
	s_mul_i32 s9, s14, 0x2400
	s_waitcnt vmcnt(11)
	ds_write_b128 v102, v[34:37]
	s_waitcnt vmcnt(10)
	ds_write_b128 v102, v[38:41] offset:8704
	ds_write_b128 v170, v[26:29]
	ds_write_b128 v170, v[30:33] offset:9216
	s_waitcnt vmcnt(9)
	v_and_b32_e32 v102, v42, v106
	v_and_b32_e32 v103, v43, v107
	v_and_b32_e32 v104, v44, v108
	v_and_b32_e32 v105, v45, v109
	ds_write_b128 v171, v[102:105] offset:17408
	s_waitcnt vmcnt(8)
	v_and_b32_e32 v102, v46, v106
	v_and_b32_e32 v103, v47, v107
	v_and_b32_e32 v104, v48, v108
	v_and_b32_e32 v105, v49, v109
	v_add_u32_e32 v106, s9, v172
	s_cmp_lg_u32 s45, 0
	ds_write_b128 v106, v[102:105]
	s_cbranch_scc1 .LBB0_617
	s_waitcnt vmcnt(4)
	v_mov_b64_e32 v[84:85], v[24:25]
	v_mov_b64_e32 v[88:89], v[20:21]
	v_mov_b64_e32 v[92:93], v[16:17]
	v_mov_b64_e32 v[96:97], v[12:13]
	v_mov_b64_e32 v[82:83], v[22:23]
	v_mov_b64_e32 v[86:87], v[18:19]
	v_mov_b64_e32 v[90:91], v[14:15]
	v_mov_b64_e32 v[94:95], v[10:11]

.LBB0_666:
	s_and_b64 vcc, exec, s[8:9]
	s_cbranch_vccnz .LBB0_668
	global_load_dword v109, v[8:9], off offset:64
	s_waitcnt vmcnt(0)
.LBB0_668:
	s_nop 0
	v_cvt_pk_bf16_f32 v2, v102, v103
	v_cvt_pk_bf16_f32 v3, v104, v105
	v_cndmask_b32_e64 v4, 0, 1, s[10:11]
	ds_write_b64 v183, v[2:3] offset:48640
	v_cvt_pk_bf16_f32 v2, v106, v107
	v_cvt_pk_bf16_f32 v3, v108, v109
	v_cmp_ne_u32_e64 s[8:9], 1, v4
	s_andn2_b64 vcc, exec, s[10:11]
	ds_write_b64 v183, v[2:3] offset:52992
	s_cbranch_vccnz .LBB0_670
	s_xor_b32 s10, s52, 1
	s_mulk_i32 s10, 0x500
	s_add_i32 s10, s10, 0
	ds_read_b128 v[74:77], v179
	v_add_u32_e32 v2, s10, v180
	v_add_u32_e32 v159, 0x1d500, v2
	ds_read_b128 v[2:5], v159
	ds_read_b128 v[6:9], v159 offset:16
	ds_read_b128 v[78:81], v179 offset:64
	s_waitcnt lgkmcnt(3)
	v_lshlrev_b32_e32 v98, 16, v74
	v_and_b32_e32 v99, 0xffff0000, v74
	s_waitcnt lgkmcnt(2)
	v_pk_mul_f32 v[2:3], v[2:3], v[98:99]
	v_lshlrev_b32_e32 v98, 16, v75
	v_and_b32_e32 v99, 0xffff0000, v75
	v_pk_mul_f32 v[4:5], v[4:5], v[98:99]
	v_cvt_pk_bf16_f32 v2, v2, v3
	v_cvt_pk_bf16_f32 v3, v4, v5
	v_lshlrev_b32_e32 v4, 16, v76
	v_and_b32_e32 v5, 0xffff0000, v76
	s_waitcnt lgkmcnt(1)
	v_pk_mul_f32 v[4:5], v[6:7], v[4:5]
	v_lshlrev_b32_e32 v6, 16, v77
	v_and_b32_e32 v7, 0xffff0000, v77
	v_pk_mul_f32 v[6:7], v[8:9], v[6:7]
	v_cvt_pk_bf16_f32 v4, v4, v5
	v_cvt_pk_bf16_f32 v5, v6, v7
	ds_read_b128 v[6:9], v196 offset:17408
	ds_read_b128 v[98:101], v196 offset:17472
	ds_read_b128 v[110:113], v196 offset:19712
	ds_read_b128 v[114:117], v196 offset:19776
	ds_read_b128 v[198:201], v196 offset:22016
	ds_read_b128 v[202:205], v196 offset:22080
	ds_read_b128 v[206:209], v196 offset:24320
	ds_read_b128 v[210:213], v159 offset:128
	ds_read_b128 v[214:217], v196 offset:24384
	s_waitcnt lgkmcnt(8)
	v_mfma_f32_16x16x32_bf16 v[6:9], v[2:5], v[6:9], 0
	v_lshlrev_b32_e32 v218, 16, v78
	v_and_b32_e32 v219, 0xffff0000, v78
	s_waitcnt lgkmcnt(1)
	v_pk_mul_f32 v[210:211], v[210:211], v[218:219]
	v_mfma_f32_16x16x32_bf16 v[110:113], v[2:5], v[110:113], 0
	v_lshlrev_b32_e32 v218, 16, v79
	v_and_b32_e32 v219, 0xffff0000, v79
	v_pk_mul_f32 v[212:213], v[212:213], v[218:219]
	v_mfma_f32_16x16x32_bf16 v[198:201], v[2:5], v[198:201], 0
	v_cvt_pk_bf16_f32 v210, v210, v211
	v_cvt_pk_bf16_f32 v211, v212, v213
	v_lshlrev_b32_e32 v212, 16, v80
	v_mfma_f32_16x16x32_bf16 v[2:5], v[2:5], v[206:209], 0
	ds_read_b128 v[206:209], v159 offset:144
	v_and_b32_e32 v213, 0xffff0000, v80
	s_waitcnt lgkmcnt(0)
	v_pk_mul_f32 v[206:207], v[206:207], v[212:213]
	s_nop 0
	v_cvt_pk_bf16_f32 v212, v206, v207
	v_lshlrev_b32_e32 v206, 16, v81
	v_and_b32_e32 v207, 0xffff0000, v81
	v_pk_mul_f32 v[206:207], v[208:209], v[206:207]
	s_nop 0
	v_cvt_pk_bf16_f32 v213, v206, v207
	s_nop 1
	v_mfma_f32_16x16x32_bf16 v[6:9], v[210:213], v[98:101], v[6:9]
	v_mfma_f32_16x16x32_bf16 v[98:101], v[210:213], v[114:117], v[110:113]
	s_nop 6
	v_cvt_pk_bf16_f32 v6, v6, v7
	v_cvt_pk_bf16_f32 v7, v8, v9
	ds_write_b64 v183, v[6:7] offset:31232
	v_mfma_f32_16x16x32_bf16 v[110:113], v[210:213], v[202:205], v[198:201]
	v_add_u32_e32 v8, v174, v188
	v_cvt_pk_bf16_f32 v6, v98, v99
	v_cvt_pk_bf16_f32 v7, v100, v101
	v_mfma_f32_16x16x32_bf16 v[2:5], v[210:213], v[214:217], v[2:5]
	ds_write_b64 v183, v[6:7] offset:35584
	s_nop 2
	v_cvt_pk_bf16_f32 v6, v110, v111
	v_cvt_pk_bf16_f32 v7, v112, v113
	ds_write_b64 v8, v[6:7] offset:31232
	s_nop 0
	v_cvt_pk_bf16_f32 v2, v2, v3
	v_cvt_pk_bf16_f32 v3, v4, v5
	ds_write_b64 v8, v[2:3] offset:35584
	ds_read_b128 v[2:5], v186 offset:17408
	ds_read_b128 v[6:9], v186 offset:17472
	ds_read_b128 v[98:101], v187 offset:26624
	ds_read_b128 v[110:113], v187 offset:26688
	s_waitcnt lgkmcnt(1)
	v_mfma_f32_16x16x32_bf16 v[2:5], v[2:5], v[98:101], 0
	s_waitcnt lgkmcnt(0)
	v_mfma_f32_16x16x32_bf16 v[98:101], v[6:9], v[110:113], v[2:5]

.LBB0_673:
	ds_read_b128 v[2:5], v193 offset:31232
	ds_read_b128 v[6:9], v192 offset:48640
	s_mul_i32 s8, s52, 0x4400
	ds_read_b128 v[110:113], v192 offset:48704
	ds_read_b128 v[114:117], v193 offset:31296
	v_add_u32_e32 v159, s8, v190
	ds_read_b128 v[198:201], v159
	ds_read_b128 v[202:205], v159 offset:64
	s_waitcnt lgkmcnt(4)
	v_mfma_f32_16x16x32_bf16 v[2:5], v[2:5], v[6:9], 0
	s_mul_i32 s8, s52, 0x500
	s_add_i32 s55, s8, 0
	s_add_i32 s55, s55, 0x1d400
	s_waitcnt lgkmcnt(1)
	v_mfma_f32_16x16x32_bf16 v[6:9], v[198:201], v[6:9], 0
	ds_read_b128 v[198:201], v193 offset:31360
	ds_read_b128 v[206:209], v193 offset:31424
	s_xor_b64 s[10:11], s[20:21], -1
	s_andn2_b64 vcc, exec, s[10:11]
	v_mfma_f32_16x16x32_bf16 v[2:5], v[114:117], v[110:113], v[2:5]
	ds_read_b128 v[114:117], v192 offset:48768
	ds_read_b128 v[210:213], v192 offset:48832
	s_waitcnt lgkmcnt(1)
	v_mfma_f32_16x16x32_bf16 v[2:5], v[198:201], v[114:117], v[2:5]
	ds_read_b128 v[198:201], v159 offset:128
	s_waitcnt lgkmcnt(1)
	v_mfma_f32_16x16x32_bf16 v[2:5], v[206:209], v[210:213], v[2:5]
	ds_read_b128 v[206:209], v159 offset:192
	v_lshl_add_u32 v159, v189, 2, s55
	v_mfma_f32_16x16x32_bf16 v[6:9], v[202:205], v[110:113], v[6:9]
	ds_read_b128 v[110:113], v159 offset:512
	s_nop 3
	v_sub_f32_e32 v5, v101, v5
	v_sub_f32_e32 v4, v100, v4
	v_sub_f32_e32 v3, v99, v3
	v_sub_f32_e32 v2, v98, v2
	s_waitcnt lgkmcnt(2)
	v_mfma_f32_16x16x32_bf16 v[6:9], v[198:201], v[114:117], v[6:9]
	v_cvt_pk_bf16_f32 v114, v2, v3
	s_waitcnt lgkmcnt(0)
	v_pk_mul_f32 v[2:3], v[2:3], v[110:111]
	v_cvt_pk_bf16_f32 v115, v4, v5
	v_pk_mul_f32 v[4:5], v[4:5], v[112:113]
	v_cvt_pk_bf16_f32 v2, v2, v3
	v_cvt_pk_bf16_f32 v3, v4, v5
	ds_write2st64_b64 v194, v[114:115], v[2:3] offset0:112 offset1:121
	ds_read_b128 v[110:113], v159
	v_mfma_f32_16x16x32_bf16 v[114:117], v[206:209], v[210:213], v[6:9]
	v_cndmask_b32_e64 v2, 0, 1, s[10:11]
	v_cmp_ne_u32_e64 s[8:9], 1, v2
	s_cbranch_vccnz .LBB0_705
	s_waitcnt vmcnt(8)
	s_xor_b32 s14, s52, 1
	s_cmp_eq_u32 s90, 0
	s_mul_i32 s10, s14, 0x4400
	s_cselect_b64 vcc, -1, 0
	v_add_u32_e32 v2, s10, v169
	v_cndmask_b32_e32 v6, v162, v161, vcc
	v_cndmask_b32_e32 v7, v164, v163, vcc
	v_cndmask_b32_e32 v8, v166, v165, vcc
	v_cndmask_b32_e32 v9, v168, v167, vcc
	s_mul_i32 s11, s14, 0x2400
	ds_write_b128 v2, v[58:61]
	ds_write_b128 v2, v[62:65] offset:8704
	ds_write_b128 v170, v[50:53]
	ds_write_b128 v170, v[54:57] offset:9216
	v_and_b32_e32 v2, v6, v66
	v_and_b32_e32 v3, v7, v67
	v_and_b32_e32 v4, v8, v68
	v_and_b32_e32 v5, v9, v69
	ds_write_b128 v171, v[2:5] offset:17408
	v_and_b32_e32 v2, v6, v70
	v_and_b32_e32 v3, v7, v71
	v_and_b32_e32 v4, v8, v72
	v_and_b32_e32 v5, v9, v73
	v_add_u32_e32 v6, s11, v172
	s_cmp_lg_u32 s45, 0
	ds_write_b128 v6, v[2:5]
	s_cbranch_scc1 .LBB0_676
	s_waitcnt vmcnt(4)
	v_mov_b64_e32 v[84:85], v[24:25]
	v_mov_b64_e32 v[88:89], v[20:21]
	v_mov_b64_e32 v[92:93], v[16:17]
	v_mov_b64_e32 v[96:97], v[12:13]
	v_mov_b64_e32 v[82:83], v[22:23]
	v_mov_b64_e32 v[86:87], v[18:19]
	v_mov_b64_e32 v[90:91], v[14:15]
	v_mov_b64_e32 v[94:95], v[10:11]

.LBB0_725:
	s_and_b64 vcc, exec, s[10:11]
	s_cbranch_vccnz .LBB0_727
	global_load_dword v9, v[106:107], off offset:64
	s_waitcnt vmcnt(0)
.LBB0_727:
	s_nop 0
	v_cvt_pk_bf16_f32 v102, v2, v3
	v_cvt_pk_bf16_f32 v103, v4, v5
	ds_write_b64 v183, v[102:103] offset:48640
	v_cvt_pk_bf16_f32 v102, v6, v7
	v_cvt_pk_bf16_f32 v103, v8, v9
	s_and_b64 vcc, exec, s[8:9]
	ds_write_b64 v183, v[102:103] offset:52992
	s_cbranch_vccnz .LBB0_729
	s_xor_b32 s10, s52, 1
	s_mulk_i32 s10, 0x500
	s_add_i32 s10, s10, 0
	ds_read_b128 v[74:77], v179
	v_add_u32_e32 v78, s10, v180
	v_add_u32_e32 v159, 0x1d500, v78
	ds_read_b128 v[98:101], v159
	ds_read_b128 v[102:105], v159 offset:16
	ds_read_b128 v[78:81], v179 offset:64
	s_waitcnt lgkmcnt(3)
	v_lshlrev_b32_e32 v106, 16, v74
	v_and_b32_e32 v107, 0xffff0000, v74
	s_waitcnt lgkmcnt(2)
	v_pk_mul_f32 v[98:99], v[98:99], v[106:107]
	v_lshlrev_b32_e32 v106, 16, v75
	v_and_b32_e32 v107, 0xffff0000, v75
	v_pk_mul_f32 v[100:101], v[100:101], v[106:107]
	v_cvt_pk_bf16_f32 v98, v98, v99
	v_cvt_pk_bf16_f32 v99, v100, v101
	v_lshlrev_b32_e32 v100, 16, v76
	v_and_b32_e32 v101, 0xffff0000, v76
	s_waitcnt lgkmcnt(1)
	v_pk_mul_f32 v[100:101], v[102:103], v[100:101]
	v_lshlrev_b32_e32 v102, 16, v77
	v_and_b32_e32 v103, 0xffff0000, v77
	v_pk_mul_f32 v[102:103], v[104:105], v[102:103]
	v_cvt_pk_bf16_f32 v100, v100, v101
	v_cvt_pk_bf16_f32 v101, v102, v103
	ds_read_b128 v[102:105], v196 offset:17408
	ds_read_b128 v[106:109], v196 offset:17472
	ds_read_b128 v[110:113], v196 offset:19712
	ds_read_b128 v[114:117], v196 offset:19776
	ds_read_b128 v[198:201], v196 offset:22016
	ds_read_b128 v[202:205], v196 offset:22080
	ds_read_b128 v[206:209], v196 offset:24320
	ds_read_b128 v[210:213], v159 offset:128
	ds_read_b128 v[214:217], v196 offset:24384
	s_waitcnt lgkmcnt(8)
	v_mfma_f32_16x16x32_bf16 v[102:105], v[98:101], v[102:105], 0
	v_lshlrev_b32_e32 v218, 16, v78
	v_and_b32_e32 v219, 0xffff0000, v78
	s_waitcnt lgkmcnt(1)
	v_pk_mul_f32 v[210:211], v[210:211], v[218:219]
	v_mfma_f32_16x16x32_bf16 v[110:113], v[98:101], v[110:113], 0
	v_lshlrev_b32_e32 v218, 16, v79
	v_and_b32_e32 v219, 0xffff0000, v79
	v_pk_mul_f32 v[212:213], v[212:213], v[218:219]
	v_mfma_f32_16x16x32_bf16 v[198:201], v[98:101], v[198:201], 0
	v_cvt_pk_bf16_f32 v210, v210, v211
	v_cvt_pk_bf16_f32 v211, v212, v213
	v_lshlrev_b32_e32 v212, 16, v80
	v_mfma_f32_16x16x32_bf16 v[98:101], v[98:101], v[206:209], 0
	ds_read_b128 v[206:209], v159 offset:144
	v_and_b32_e32 v213, 0xffff0000, v80
	s_waitcnt lgkmcnt(0)
	v_pk_mul_f32 v[206:207], v[206:207], v[212:213]
	s_nop 0
	v_cvt_pk_bf16_f32 v212, v206, v207
	v_lshlrev_b32_e32 v206, 16, v81
	v_and_b32_e32 v207, 0xffff0000, v81
	v_pk_mul_f32 v[206:207], v[208:209], v[206:207]
	s_nop 0
	v_cvt_pk_bf16_f32 v213, v206, v207
	s_nop 1
	v_mfma_f32_16x16x32_bf16 v[102:105], v[210:213], v[106:109], v[102:105]
	v_mfma_f32_16x16x32_bf16 v[106:109], v[210:213], v[114:117], v[110:113]
	s_nop 6
	v_cvt_pk_bf16_f32 v102, v102, v103
	v_cvt_pk_bf16_f32 v103, v104, v105
	ds_write_b64 v183, v[102:103] offset:31232
	v_mfma_f32_16x16x32_bf16 v[110:113], v[210:213], v[202:205], v[198:201]
	v_add_u32_e32 v104, v174, v188
	v_cvt_pk_bf16_f32 v102, v106, v107
	v_cvt_pk_bf16_f32 v103, v108, v109
	v_mfma_f32_16x16x32_bf16 v[98:101], v[210:213], v[214:217], v[98:101]
	ds_write_b64 v183, v[102:103] offset:35584
	s_nop 2
	v_cvt_pk_bf16_f32 v102, v110, v111
	v_cvt_pk_bf16_f32 v103, v112, v113
	ds_write_b64 v104, v[102:103] offset:31232
	s_nop 0
	v_cvt_pk_bf16_f32 v98, v98, v99
	v_cvt_pk_bf16_f32 v99, v100, v101
	ds_write_b64 v104, v[98:99] offset:35584
	ds_read_b128 v[98:101], v186 offset:17408
	ds_read_b128 v[102:105], v186 offset:17472
	ds_read_b128 v[106:109], v187 offset:26624
	ds_read_b128 v[110:113], v187 offset:26688
	s_waitcnt lgkmcnt(1)
	v_mfma_f32_16x16x32_bf16 v[98:101], v[98:101], v[106:109], 0
	s_waitcnt lgkmcnt(0)
	v_mfma_f32_16x16x32_bf16 v[98:101], v[102:105], v[110:113], v[98:101]
